# v13 + HGRN2 output unit: one load per lane touches next chunk's 64 cache lines per wave while the current chunk is processed
# baseline (speedup 1.0000x reference)
; #define LAS __attribute__((address_space(3)))
; #define LDS_SYNC() do { asm volatile("s_waitcnt lgkmcnt(0)" ::: "memory"); __builtin_amdgcn_s_barrier(); asm volatile("" ::: "memory"); } while (0)
; __device__ __forceinline__ unsigned pk2(float lo, float hi) { return pg8::cvt_pk_bf16(lo, hi); }
; template <bool OUT>
; __device__ __forceinline__ void hgrn_unit(int unit, LAS unsigned char* lds, const float* HLF, const bf16* HQ, const bf16* HV, const bf16* HG, bf16* MIX, float* UBUF, float* DTOT, const float* SST, gu32* rdy4 = nullptr) {
;     ...
;             const int ti = wid & 1, vi = wid >> 1;
; #pragma unroll
;             for (int r = 0; r < 16; ++r) oacc[r] = 0.f;
; #pragma unroll
;             for (int ks = 0; ks < 4; ++ks) { const bf16x8 a = *(const LAS bf16x8*)(PP + (32 * ti + r32) * 72 + 16 * ks + 8 * hi), bb = *(const LAS bf16x8*)(VT + (32 * vi + r32) * 72 + 16 * ks + 8 * hi); oacc = MFMA32(a, bb, oacc); }
; #pragma unroll
;             for (int ks = 0; ks < 8; ++ks) { const bf16x8 a = *(const LAS bf16x8*)(QT + (32 * ti + r32) * 136 + 16 * ks + 8 * hi), bb = *(const LAS bf16x8*)(ST + (32 * vi + r32) * 136 + 16 * ks + 8 * hi); oacc = MFMA32(a, bb, oacc); }
;         }
;         {
;             float dk[16];
; #pragma unroll
;             for (int r = 0; r < 16; ++r) dk[r] = DEC[32 * ki + crow(r, hi)];
; #pragma unroll
;             for (int j = 0; j < 2; ++j)
; #pragma unroll
;                 for (int r = 0; r < 16; ++r) S[j][r] *= dk[r];
; #pragma unroll
;             for (int ks = 0; ks < 4; ++ks) { const bf16x8 a = *(const LAS bf16x8*)(KET + (32 * ki + r32) * 72 + 16 * ks + 8 * hi);
; #pragma unroll
;                 for (int j = 0; j < 2; ++j) { const bf16x8 bb = *(const LAS bf16x8*)(VT + (32 * (vi0 + j) + r32) * 72 + 16 * ks + 8 * hi); S[j] = MFMA32(a, bb, S[j]); } }
;         }
;         if (OUT) {
;             LDS_SYNC();
;             const int ti = wid & 1, vi = wid >> 1;
; #pragma unroll
;             for (int r = 0; r < 16; ++r) OS[(32 * ti + crow(r, hi)) * 132 + 32 * vi + r32] = oacc[r];
; #pragma unroll
;             for (int j = 0; j < 2; ++j)
; #pragma unroll
;                 for (int g = 0; g < 4; ++g) *(LAS v2u*)(ST + (32 * (vi0 + j) + r32) * 136 + 32 * ki + 8 * g + 4 * hi) = (v2u){pk2(S[j][4 * g], S[j][4 * g + 1]), pk2(S[j][4 * g + 2], S[j][4 * g + 3])};
.LBB0_585:
	s_waitcnt lgkmcnt(0)
	s_barrier
	ds_read_b128 v[34:37], v86
	ds_read_b128 v[38:41], v87 offset:53248
	ds_read_b128 v[98:101], v86 offset:32
	ds_read_b128 v[102:105], v87 offset:53280
	s_waitcnt lgkmcnt(2)
	v_mfma_f32_32x32x16_bf16 v[34:49], v[34:37], v[38:41], 0
	s_waitcnt lgkmcnt(0)
	v_mfma_f32_32x32x16_bf16 v[34:49], v[98:101], v[102:105], v[34:49]
	ds_read_b128 v[98:101], v86 offset:64
	ds_read_b128 v[102:105], v87 offset:53312
	ds_read_b128 v[106:109], v86 offset:96
	ds_read_b128 v[110:113], v87 offset:53344
	s_waitcnt lgkmcnt(2)
	v_mfma_f32_32x32x16_bf16 v[34:49], v[98:101], v[102:105], v[34:49]
	s_waitcnt lgkmcnt(0)
	v_mfma_f32_32x32x16_bf16 v[34:49], v[106:109], v[110:113], v[34:49]
	ds_read_b128 v[98:101], v88
	ds_read_b128 v[102:105], v89
	ds_read_b128 v[106:109], v88 offset:32
	ds_read_b128 v[110:113], v89 offset:32
	s_waitcnt lgkmcnt(2)
	v_mfma_f32_32x32x16_bf16 v[34:49], v[98:101], v[102:105], v[34:49]
	s_waitcnt lgkmcnt(0)
	v_mfma_f32_32x32x16_bf16 v[34:49], v[106:109], v[110:113], v[34:49]
	ds_read_b128 v[98:101], v88 offset:64
	ds_read_b128 v[102:105], v89 offset:64
	ds_read_b128 v[106:109], v88 offset:96
	ds_read_b128 v[110:113], v89 offset:96
	s_waitcnt lgkmcnt(2)
	v_mfma_f32_32x32x16_bf16 v[34:49], v[98:101], v[102:105], v[34:49]
	s_waitcnt lgkmcnt(0)
	v_mfma_f32_32x32x16_bf16 v[34:49], v[106:109], v[110:113], v[34:49]
	ds_read_b128 v[98:101], v88 offset:128
	ds_read_b128 v[102:105], v89 offset:128
	ds_read_b128 v[106:109], v88 offset:160
	ds_read_b128 v[110:113], v89 offset:160
	s_waitcnt lgkmcnt(2)
	v_mfma_f32_32x32x16_bf16 v[34:49], v[98:101], v[102:105], v[34:49]
	ds_read_b128 v[98:101], v88 offset:192
	ds_read_b128 v[102:105], v88 offset:224
	ds_read_b128 v[114:117], v89 offset:192
	ds_read_b128 v[118:121], v89 offset:224
	ds_read_b128 v[122:125], v90
	ds_read_b128 v[126:129], v90 offset:32
	ds_read_b128 v[130:133], v90 offset:64
	ds_read_b128 v[134:137], v90 offset:96
	s_waitcnt lgkmcnt(3)
	v_pk_mul_f32 v[2:3], v[2:3], v[122:123]
	v_pk_mul_f32 v[4:5], v[4:5], v[124:125]
	s_waitcnt lgkmcnt(2)
	v_pk_mul_f32 v[6:7], v[6:7], v[126:127]
	v_pk_mul_f32 v[8:9], v[8:9], v[128:129]
	s_waitcnt lgkmcnt(1)
	v_pk_mul_f32 v[10:11], v[10:11], v[130:131]
	v_mfma_f32_32x32x16_bf16 v[34:49], v[106:109], v[110:113], v[34:49]
	ds_read_b128 v[106:109], v91 offset:34816
	ds_read_b128 v[110:113], v91 offset:34848
	ds_read_b128 v[138:141], v92 offset:53248
	ds_read_b128 v[142:145], v92 offset:53280
	v_mul_f32_e64 v12, v12, v132
	v_mul_f32_e64 v13, v13, v133
	s_waitcnt lgkmcnt(4)
	v_pk_mul_f32 v[14:15], v[14:15], v[134:135]
	v_pk_mul_f32 v[16:17], v[16:17], v[136:137]
	v_pk_mul_f32 v[18:19], v[18:19], v[122:123]
	v_pk_mul_f32 v[20:21], v[20:21], v[124:125]
	v_pk_mul_f32 v[22:23], v[22:23], v[126:127]
	v_mfma_f32_32x32x16_bf16 v[34:49], v[98:101], v[114:117], v[34:49]
	ds_read_b128 v[98:101], v93 offset:53248
	ds_read_b128 v[114:117], v93 offset:53280
	v_mul_f32_e64 v24, v24, v128
	v_mul_f32_e64 v25, v25, v129
	v_mul_f32_e64 v26, v26, v130
	v_mul_f32_e64 v27, v27, v131
	v_pk_mul_f32 v[28:29], v[28:29], v[132:133]
	v_pk_mul_f32 v[30:31], v[30:31], v[134:135]
	v_pk_mul_f32 v[32:33], v[32:33], v[136:137]
	s_waitcnt lgkmcnt(3)
	v_mfma_f32_32x32x16_bf16 v[2:17], v[106:109], v[138:141], v[2:17]
	s_waitcnt lgkmcnt(1)
	v_mfma_f32_32x32x16_bf16 v[18:33], v[106:109], v[98:101], v[18:33]
	v_mfma_f32_32x32x16_bf16 v[2:17], v[110:113], v[142:145], v[2:17]
	s_waitcnt lgkmcnt(0)
	v_mfma_f32_32x32x16_bf16 v[18:33], v[110:113], v[114:117], v[18:33]
	ds_read_b128 v[98:101], v91 offset:34880
	ds_read_b128 v[106:109], v91 offset:34912
	ds_read_b128 v[110:113], v92 offset:53312
	ds_read_b128 v[114:117], v92 offset:53344
	ds_read_b128 v[122:125], v93 offset:53312
	ds_read_b128 v[126:129], v93 offset:53344
	s_waitcnt lgkmcnt(0)
	s_barrier
	s_waitcnt lgkmcnt(3)
	v_mfma_f32_32x32x16_bf16 v[2:17], v[98:101], v[110:113], v[2:17]
	v_mfma_f32_32x32x16_bf16 v[34:49], v[102:105], v[118:121], v[34:49]
	s_waitcnt lgkmcnt(1)
	v_mfma_f32_32x32x16_bf16 v[18:33], v[98:101], v[122:125], v[18:33]
	s_nop 9
	ds_write2_b32 v94, v34, v35 offset1:132
	v_add_u32_e32 v34, 0x400, v94
	ds_write2_b32 v34, v36, v37 offset0:8 offset1:140
	v_add_u32_e32 v34, 0x1000, v94
	ds_write2_b32 v34, v38, v39 offset0:32 offset1:164
	v_add_u32_e32 v34, 0x1400, v94
	ds_write2_b32 v34, v40, v41 offset0:40 offset1:172
	v_mfma_f32_32x32x16_bf16 v[2:17], v[106:109], v[114:117], v[2:17]
	v_add_u32_e32 v34, 0x2000, v94
	ds_write2_b32 v34, v42, v43 offset0:64 offset1:196
	v_add_u32_e32 v34, 0x2400, v94
	ds_write2_b32 v34, v44, v45 offset0:72 offset1:204
	v_add_u32_e32 v34, 0x3000, v94
	ds_write2_b32 v34, v46, v47 offset0:96 offset1:228
	v_add_u32_e32 v34, 0x3400, v94
	s_waitcnt lgkmcnt(7)
	v_mfma_f32_32x32x16_bf16 v[18:33], v[106:109], v[126:129], v[18:33]
	ds_write2_b32 v34, v48, v49 offset0:104 offset1:236
	s_nop 1
	v_cvt_pk_bf16_f32 v34, v2, v3
	v_cvt_pk_bf16_f32 v35, v4, v5
	v_cvt_pk_bf16_f32 v36, v6, v7
	v_cvt_pk_bf16_f32 v37, v8, v9
	ds_write2_b64 v95, v[34:35], v[36:37] offset1:2
	v_cvt_pk_bf16_f32 v34, v10, v11
	v_cvt_pk_bf16_f32 v35, v12, v13
	v_cvt_pk_bf16_f32 v36, v14, v15
	v_cvt_pk_bf16_f32 v37, v16, v17
	ds_write2_b64 v95, v[34:35], v[36:37] offset0:4 offset1:6
	v_cvt_pk_bf16_f32 v34, v18, v19
	v_cvt_pk_bf16_f32 v35, v20, v21
	v_cvt_pk_bf16_f32 v36, v22, v23
	v_cvt_pk_bf16_f32 v37, v24, v25
	v_add_u32_e32 v106, s58, v81
	ds_write2_b64 v96, v[34:35], v[36:37] offset1:2
	v_cvt_pk_bf16_f32 v34, v26, v27
	v_cvt_pk_bf16_f32 v35, v28, v29
	v_cvt_pk_bf16_f32 v36, v30, v31
	v_cvt_pk_bf16_f32 v37, v32, v33
	v_ashrrev_i32_e32 v107, 31, v106
	ds_write2_b64 v96, v[34:35], v[36:37] offset0:4 offset1:6
	v_lshlrev_b64 v[34:35], 10, v[106:107]
	s_waitcnt lgkmcnt(0)
	s_barrier
; __device__ __forceinline__ void store16_wt(void* p, u32x4 v) { asm volatile("global_store_dwordx4 %0, %1, off sc1\n\ts_nop 1" :: "v"(p), "v"(v) : "memory"); }
; #define LAS __attribute__((address_space(3)))
; #define LDS_SYNC() do { asm volatile("s_waitcnt lgkmcnt(0)" ::: "memory"); __builtin_amdgcn_s_barrier(); asm volatile("" ::: "memory"); } while (0)
; __device__ __forceinline__ unsigned pk2(float lo, float hi) { return pg8::cvt_pk_bf16(lo, hi); }
; template <bool OUT>
; __device__ __forceinline__ void hgrn_unit(int unit, LAS unsigned char* lds, const float* HLF, const bf16* HQ, const bf16* HV, const bf16* HG, bf16* MIX, float* UBUF, float* DTOT, const float* SST, gu32* rdy4 = nullptr) {
;     ...
;             LDS_SYNC();
;             const int t = tid >> 3, seg = tid & 7; const int row = row_base + 64 * c + t;
;             f32x4 o4[4]; float ss = 0.f;
; #pragma unroll
;             for (int i = 0; i < 4; ++i) { o4[i] = *(const LAS f32x4*)(OS + t * 132 + 16 * seg + 4 * i); ss += (o4[i][0] * o4[i][0] + o4[i][1] * o4[i][1]) + (o4[i][2] * o4[i][2] + o4[i][3] * o4[i][3]); }
;             ss += __shfl_xor(ss, 1); ss += __shfl_xor(ss, 2); ss += __shfl_xor(ss, 4);
;             const float rstd = rsqrtf(ss * (1.0f / 128.0f) + EPSF);
;             const v4u g0 = *(const v4u*)(HG + (size_t)row * 512 + col0 + 16 * seg), g1 = *(const v4u*)(HG + (size_t)row * 512 + col0 + 16 * seg + 8);
;             const unsigned gw[8] = {g0.x, g0.y, g0.z, g0.w, g1.x, g1.y, g1.z, g1.w}; unsigned ow[8];
; #pragma unroll
;             for (int i = 0; i < 8; ++i) { const float a = o4[i >> 1][2 * (i & 1)] * rstd * __builtin_bit_cast(float, gw[i] << 16), bq = o4[i >> 1][2 * (i & 1) + 1] * rstd * __builtin_bit_cast(float, gw[i] & 0xffff0000u); ow[i] = pk2(a, bq); }
;             pg8::store16_wt(MIX + (size_t)row * 1024 + 512 + col0 + 16 * seg, (v4u){ow[0], ow[1], ow[2], ow[3]}); pg8::store16_wt(MIX + (size_t)row * 1024 + 512 + col0 + 16 * seg + 8, (v4u){ow[4], ow[5], ow[6], ow[7]});
;         }
;         LDS_SYNC();
	v_lshl_add_u64 v[42:43], v[60:61], 0, v[34:35]
	ds_read_b128 v[38:41], v78
	ds_read_b128 v[46:49], v78 offset:16
	ds_read_b128 v[98:101], v78 offset:32
	ds_read_b128 v[102:105], v78 offset:48
	s_add_i32 s58, s58, 64
	s_cmpk_eq_i32 s58, 0x100
	s_waitcnt lgkmcnt(3)
	v_pk_mul_f32 v[108:109], v[40:41], v[40:41]
	v_pk_mul_f32 v[110:111], v[38:39], v[38:39]
	s_waitcnt lgkmcnt(0)
	v_mul_f32_e32 v97, v102, v102
	v_pk_mov_b32 v[112:113], v[110:111], v[108:109] op_sel:[1,0]
	v_mov_b32_e32 v111, v109
	v_pk_add_f32 v[108:109], v[112:113], v[110:111]
	v_pk_mul_f32 v[110:111], v[48:49], v[48:49]
	v_pk_mul_f32 v[112:113], v[46:47], v[46:47]
	v_pk_add_f32 v[108:109], v[108:109], v[108:109] op_sel:[0,1] op_sel_hi:[1,0]
	v_pk_mov_b32 v[114:115], v[112:113], v[110:111] op_sel:[1,0]
	v_mov_b32_e32 v113, v111
	v_pk_add_f32 v[110:111], v[114:115], v[112:113]
	v_mul_f32_e32 v112, v103, v103
	v_pk_add_f32 v[110:111], v[110:111], v[110:111] op_sel:[0,1] op_sel_hi:[1,0]
	v_mov_b32_e32 v109, v97
	v_mov_b32_e32 v111, v112
	v_pk_add_f32 v[108:109], v[108:109], v[110:111]
	v_mul_f32_e32 v110, v99, v99
	v_mul_f32_e32 v113, v104, v104
	v_pk_fma_f32 v[110:111], v[98:99], v[98:99], v[110:111] op_sel_hi:[1,1,0]
	v_mul_f32_e32 v112, v101, v101
	v_mul_f32_e32 v114, v105, v105
	v_mov_b32_e32 v111, v113
	v_pk_fma_f32 v[112:113], v[100:101], v[100:101], v[112:113] op_sel_hi:[1,1,0]
	s_nop 0
	v_mov_b32_e32 v113, v114
	v_pk_add_f32 v[110:111], v[110:111], v[112:113]
	s_nop 0
	v_pk_add_f32 v[108:109], v[108:109], v[110:111]
	s_waitcnt vmcnt(2)
	v_lshlrev_b32_e32 v110, 16, v200
	v_add_f32_e32 v97, v108, v109
	v_and_b32_e32 v109, 64, v80
	v_xor_b32_e32 v108, 1, v80
	v_add_u32_e32 v109, 64, v109
	v_cmp_lt_i32_e32 vcc, v108, v109
	v_and_b32_e32 v111, 0xffff0000, v200
	s_nop 0
	v_cndmask_b32_e32 v108, v80, v108, vcc
	v_lshlrev_b32_e32 v108, 2, v108
	ds_bpermute_b32 v108, v108, v97
	s_waitcnt lgkmcnt(0)
	v_add_f32_e32 v97, v97, v108
	v_xor_b32_e32 v108, 2, v80
	v_cmp_lt_i32_e32 vcc, v108, v109
	s_nop 1
	v_cndmask_b32_e32 v108, v80, v108, vcc
	v_lshlrev_b32_e32 v108, 2, v108
	ds_bpermute_b32 v108, v108, v97
	s_waitcnt lgkmcnt(0)
	v_add_f32_e32 v97, v97, v108
	v_xor_b32_e32 v108, 4, v80
	v_cmp_lt_i32_e32 vcc, v108, v109
	s_nop 1
	v_cndmask_b32_e32 v108, v80, v108, vcc
	v_lshlrev_b32_e32 v108, 2, v108
	ds_bpermute_b32 v108, v108, v97
	s_waitcnt lgkmcnt(0)
	v_add_f32_e32 v97, v97, v108
	v_fmamk_f32 v97, v97, 0x3c000000, v79
	v_mul_f32_e32 v108, 0x4b800000, v97
	v_cmp_gt_f32_e32 vcc, s55, v97
	s_nop 1
	v_cndmask_b32_e32 v97, v97, v108, vcc
	v_rsq_f32_e32 v97, v97
	s_nop 0
	v_mul_f32_e32 v108, 0x45800000, v97
	v_cndmask_b32_e32 v108, v97, v108, vcc
	v_pk_mul_f32 v[38:39], v[38:39], v[108:109] op_sel_hi:[1,0]
	v_pk_mul_f32 v[40:41], v[40:41], v[108:109] op_sel_hi:[1,0]
	v_pk_mul_f32 v[38:39], v[38:39], v[110:111]
	s_nop 0
	v_cvt_pk_bf16_f32 v34, v38, v39
	v_lshlrev_b32_e32 v38, 16, v201
	v_and_b32_e32 v39, 0xffff0000, v201
	v_pk_mul_f32 v[38:39], v[40:41], v[38:39]
	v_lshlrev_b32_e32 v40, 16, v202
	v_cvt_pk_bf16_f32 v35, v38, v39
	v_pk_mul_f32 v[38:39], v[46:47], v[108:109] op_sel_hi:[1,0]
	v_and_b32_e32 v41, 0xffff0000, v202
	v_pk_mul_f32 v[38:39], v[38:39], v[40:41]
	v_lshlrev_b32_e32 v40, 16, v203
	v_cvt_pk_bf16_f32 v36, v38, v39
	v_pk_mul_f32 v[38:39], v[48:49], v[108:109] op_sel_hi:[1,0]
	v_and_b32_e32 v41, 0xffff0000, v203
	v_pk_mul_f32 v[38:39], v[38:39], v[40:41]
	s_waitcnt vmcnt(1)
	v_lshlrev_b32_e32 v40, 16, v204
	v_cvt_pk_bf16_f32 v37, v38, v39
	v_pk_mul_f32 v[38:39], v[98:99], v[108:109] op_sel_hi:[1,0]
	v_and_b32_e32 v41, 0xffff0000, v204
	v_pk_mul_f32 v[38:39], v[38:39], v[40:41]
	v_pk_mul_f32 v[40:41], v[100:101], v[108:109] op_sel_hi:[1,0]
	v_lshlrev_b32_e32 v42, 16, v205
	v_and_b32_e32 v43, 0xffff0000, v205
	v_pk_mul_f32 v[40:41], v[40:41], v[42:43]
	v_cvt_pk_bf16_f32 v38, v38, v39
	v_cvt_pk_bf16_f32 v39, v40, v41
	v_pk_mul_f32 v[40:41], v[102:103], v[108:109] op_sel_hi:[1,0]
	v_lshlrev_b32_e32 v42, 16, v206
	v_and_b32_e32 v43, 0xffff0000, v206
	v_pk_mul_f32 v[40:41], v[40:41], v[42:43]
	v_pk_mul_f32 v[42:43], v[104:105], v[108:109] op_sel_hi:[1,0]
	v_lshlrev_b32_e32 v44, 16, v207
	v_and_b32_e32 v45, 0xffff0000, v207
	v_pk_mul_f32 v[42:43], v[42:43], v[44:45]
	v_cvt_pk_bf16_f32 v40, v40, v41
	v_cvt_pk_bf16_f32 v41, v42, v43
	v_lshlrev_b64 v[42:43], 11, v[106:107]
	v_lshl_add_u64 v[42:43], s[62:63], 0, v[42:43]
	v_lshl_add_u64 v[42:43], v[42:43], 0, s[70:71]
	v_lshl_add_u64 v[42:43], v[42:43], 0, v[52:53]
	v_lshl_add_u64 v[44:45], v[42:43], 0, s[72:73]
	global_store_dwordx4 v[44:45], v[34:37], off sc1
	s_nop 1
	v_lshl_add_u64 v[34:35], v[42:43], 0, s[74:75]
	global_store_dwordx4 v[34:35], v[38:41], off sc1
	s_nop 1
	s_waitcnt lgkmcnt(0)
	s_barrier
	s_cbranch_scc1 .LBB0_596
; template <bool OUT>
; __device__ __forceinline__ void hgrn_unit(int unit, LAS unsigned char* lds, const float* HLF, const bf16* HQ, const bf16* HV, const bf16* HG, bf16* MIX, float* UBUF, float* DTOT, const float* SST, gu32* rdy4 = nullptr) {
;     ...
;     for (int c = 0; c < 4; ++c) {
;         const int rows = row_base + 64 * c + 16 * tq;
;         float cs[16]; unsigned short vv[16], qq[16];
; #pragma unroll
;         for (int i = 0; i < 16; ++i) { cs[i] = HLF[(size_t)(rows + i) * 512 + col0 + kx]; vv[i] = HV[(size_t)(rows + i) * 512 + col0 + kx]; if (OUT) qq[i] = HQ[(size_t)(rows + i) * 512 + col0 + kx]; }
.LBB0_586:
	v_add_u32_e32 v38, s58, v82
	v_add_u32_e32 v36, 1, v38
	v_ashrrev_i32_e32 v37, 31, v36
	v_lshlrev_b64 v[36:37], 9, v[36:37]
	v_or_b32_e32 v36, v36, v58
	v_lshl_add_u64 v[44:45], v[36:37], 2, s[64:65]
	v_lshlrev_b64 v[46:47], 1, v[36:37]
	v_add_u32_e32 v36, 2, v38
	v_ashrrev_i32_e32 v39, 31, v38
	v_ashrrev_i32_e32 v37, 31, v36
	v_lshlrev_b64 v[34:35], 9, v[38:39]
	v_lshlrev_b64 v[36:37], 9, v[36:37]
	v_or_b32_e32 v34, v34, v58
	v_or_b32_e32 v36, v36, v58
	v_lshl_add_u64 v[40:41], v[34:35], 2, s[64:65]
	v_lshlrev_b64 v[34:35], 1, v[34:35]
	v_lshl_add_u64 v[48:49], s[68:69], 0, v[46:47]
	v_lshl_add_u64 v[98:99], v[36:37], 2, s[64:65]
	v_lshlrev_b64 v[36:37], 1, v[36:37]
	v_lshl_add_u64 v[42:43], s[68:69], 0, v[34:35]
	v_lshl_add_u64 v[100:101], s[68:69], 0, v[36:37]
	global_load_dword v120, v[40:41], off
	global_load_ushort v121, v[42:43], off
	global_load_dword v122, v[44:45], off
	global_load_ushort v123, v[48:49], off
	global_load_dword v124, v[98:99], off
	global_load_ushort v125, v[100:101], off
	v_add_u32_e32 v40, 3, v38
	v_add_u32_e32 v48, 4, v38
	v_ashrrev_i32_e32 v41, 31, v40
	v_ashrrev_i32_e32 v49, 31, v48
	v_add_u32_e32 v102, 5, v38
	v_lshlrev_b64 v[40:41], 9, v[40:41]
	v_lshlrev_b64 v[48:49], 9, v[48:49]
	v_ashrrev_i32_e32 v103, 31, v102
	v_or_b32_e32 v40, v40, v58
	v_or_b32_e32 v48, v48, v58
	v_lshlrev_b64 v[102:103], 9, v[102:103]
	v_lshl_add_u64 v[42:43], v[40:41], 2, s[64:65]
	v_lshlrev_b64 v[40:41], 1, v[40:41]
	v_lshl_add_u64 v[98:99], v[48:49], 2, s[64:65]
	v_lshlrev_b64 v[48:49], 1, v[48:49]
	v_or_b32_e32 v102, v102, v58
	v_lshl_add_u64 v[44:45], s[68:69], 0, v[40:41]
	v_lshl_add_u64 v[100:101], s[68:69], 0, v[48:49]
	v_lshl_add_u64 v[104:105], v[102:103], 2, s[64:65]
	global_load_dword v126, v[42:43], off
	global_load_ushort v127, v[44:45], off
	global_load_dword v128, v[98:99], off
	global_load_ushort v129, v[100:101], off
	global_load_dword v130, v[104:105], off
	v_add_u32_e32 v98, 6, v38
	v_add_u32_e32 v104, 7, v38
	v_ashrrev_i32_e32 v99, 31, v98
	v_ashrrev_i32_e32 v105, 31, v104
	v_lshlrev_b64 v[98:99], 9, v[98:99]
	v_lshlrev_b64 v[104:105], 9, v[104:105]
	v_lshlrev_b64 v[42:43], 1, v[102:103]
	v_or_b32_e32 v98, v98, v58
	v_or_b32_e32 v104, v104, v58
	v_lshl_add_u64 v[44:45], s[68:69], 0, v[42:43]
	v_lshl_add_u64 v[100:101], v[98:99], 2, s[64:65]
	v_lshlrev_b64 v[98:99], 1, v[98:99]
	v_lshl_add_u64 v[106:107], v[104:105], 2, s[64:65]
	v_lshlrev_b64 v[104:105], 1, v[104:105]
	v_lshl_add_u64 v[102:103], s[68:69], 0, v[98:99]
	v_lshl_add_u64 v[108:109], s[68:69], 0, v[104:105]
	global_load_ushort v131, v[44:45], off
	global_load_dword v132, v[100:101], off
	global_load_ushort v133, v[102:103], off
	global_load_dword v134, v[106:107], off
	global_load_ushort v135, v[108:109], off
	v_add_u32_e32 v44, 8, v38
	v_add_u32_e32 v106, 9, v38
	v_add_u32_e32 v112, 10, v38
	v_ashrrev_i32_e32 v45, 31, v44
	v_ashrrev_i32_e32 v107, 31, v106
	v_ashrrev_i32_e32 v113, 31, v112
	v_lshlrev_b64 v[44:45], 9, v[44:45]
	v_lshlrev_b64 v[106:107], 9, v[106:107]
	v_lshlrev_b64 v[112:113], 9, v[112:113]
	v_or_b32_e32 v44, v44, v58
	v_or_b32_e32 v106, v106, v58
	v_or_b32_e32 v112, v112, v58
	v_lshl_add_u64 v[100:101], v[44:45], 2, s[64:65]
	v_lshlrev_b64 v[44:45], 1, v[44:45]
	v_lshl_add_u64 v[108:109], v[106:107], 2, s[64:65]
	v_lshlrev_b64 v[106:107], 1, v[106:107]
	v_lshl_add_u64 v[114:115], v[112:113], 2, s[64:65]
	v_lshlrev_b64 v[112:113], 1, v[112:113]
	v_lshl_add_u64 v[102:103], s[68:69], 0, v[44:45]
	v_lshl_add_u64 v[110:111], s[68:69], 0, v[106:107]
	v_lshl_add_u64 v[116:117], s[68:69], 0, v[112:113]
	global_load_dword v136, v[100:101], off
	global_load_ushort v137, v[102:103], off
	global_load_dword v138, v[108:109], off
	global_load_ushort v139, v[110:111], off
	global_load_dword v140, v[114:115], off
	global_load_ushort v141, v[116:117], off
	v_add_u32_e32 v100, 11, v38
	v_ashrrev_i32_e32 v101, 31, v100
	v_add_u32_e32 v110, 12, v38
	v_lshlrev_b64 v[100:101], 9, v[100:101]
	v_ashrrev_i32_e32 v111, 31, v110
	v_or_b32_e32 v100, v100, v58
	v_lshlrev_b64 v[110:111], 9, v[110:111]
	v_lshl_add_u64 v[102:103], v[100:101], 2, s[64:65]
	v_lshlrev_b64 v[100:101], 1, v[100:101]
	v_or_b32_e32 v110, v110, v58
	v_lshl_add_u64 v[108:109], s[68:69], 0, v[100:101]
	v_lshlrev_b64 v[114:115], 1, v[110:111]
	v_lshl_add_u64 v[116:117], s[68:69], 0, v[114:115]
	global_load_ushort v142, v[108:109], off
	global_load_ushort v143, v[116:117], off
	v_add_u32_e32 v108, 13, v38
	v_ashrrev_i32_e32 v109, 31, v108
	v_lshlrev_b64 v[108:109], 9, v[108:109]
	v_or_b32_e32 v108, v108, v58
	v_lshlrev_b64 v[116:117], 1, v[108:109]
	v_lshl_add_u64 v[118:119], s[68:69], 0, v[116:117]
	global_load_ushort v118, v[118:119], off
	v_lshl_add_u64 v[110:111], v[110:111], 2, s[64:65]
	v_lshl_add_u64 v[108:109], v[108:109], 2, s[64:65]
	global_load_dword v119, v[102:103], off
	global_load_dword v144, v[110:111], off
	global_load_dword v145, v[108:109], off
	v_add_u32_e32 v102, 14, v38
	v_ashrrev_i32_e32 v103, 31, v102
	v_add_u32_e32 v38, 15, v38
	v_lshlrev_b64 v[102:103], 9, v[102:103]
	v_ashrrev_i32_e32 v39, 31, v38
	v_or_b32_e32 v102, v102, v58
	v_lshlrev_b64 v[38:39], 9, v[38:39]
	v_lshl_add_u64 v[108:109], v[102:103], 2, s[64:65]
	v_or_b32_e32 v38, v38, v58
	v_lshl_add_u64 v[110:111], v[38:39], 2, s[64:65]
	global_load_dword v146, v[108:109], off
	global_load_dword v97, v[110:111], off
	v_lshlrev_b64 v[102:103], 1, v[102:103]
	v_lshlrev_b64 v[110:111], 1, v[38:39]
	v_lshl_add_u64 v[108:109], s[68:69], 0, v[102:103]
	v_lshl_add_u64 v[38:39], s[68:69], 0, v[110:111]
	global_load_ushort v108, v[108:109], off
	s_nop 0
	global_load_ushort v109, v[38:39], off
	v_lshl_add_u64 v[38:39], s[66:67], 0, v[46:47]
	v_lshl_add_u64 v[34:35], s[66:67], 0, v[34:35]
	global_load_ushort v147, v[38:39], off
	global_load_ushort v148, v[34:35], off
	v_lshl_add_u64 v[46:47], s[66:67], 0, v[36:37]
	v_lshl_add_u64 v[36:37], s[66:67], 0, v[40:41]
	v_lshl_add_u64 v[38:39], s[66:67], 0, v[48:49]
	v_lshl_add_u64 v[40:41], s[66:67], 0, v[104:105]
	s_waitcnt vmcnt(30)
; #define LDS_SYNC() do { asm volatile("s_waitcnt lgkmcnt(0)" ::: "memory"); __builtin_amdgcn_s_barrier(); asm volatile("" ::: "memory"); } while (0)
; __device__ __forceinline__ unsigned f2bf(float f) { unsigned u = __builtin_bit_cast(unsigned, f); return (u + 0x7fffu + ((u >> 16) & 1u)) >> 16; }
; __device__ __forceinline__ unsigned pk2(float lo, float hi) { return pg8::cvt_pk_bf16(lo, hi); }
; __device__ __forceinline__ float ex2(float x) { return __builtin_amdgcn_exp2f(x); }
; template <bool OUT>
; __device__ __forceinline__ void hgrn_unit(int unit, LAS unsigned char* lds, const float* HLF, const bf16* HQ, const bf16* HV, const bf16* HG, bf16* MIX, float* UBUF, float* DTOT, const float* SST, gu32* rdy4 = nullptr) {
;     ...
;         float lf[16];
; #pragma unroll
;         for (int i = 0; i < 16; ++i) { lf[i] = cs[i]; if (i) cs[i] += cs[i - 1]; }
;         TOT[tq * 128 + kx] = cs[15];
;         LDS_SYNC();
;         float off = 0.f, blast = 0.f;
; #pragma unroll
;         for (int q = 0; q < 4; ++q) { const float t = TOT[q * 128 + kx]; if (q < tq) off += t; blast += t; }
;         unsigned kew[8], vtw[8];
; #pragma unroll
;         for (int i = 0; i < 16; i += 2) {
;             float ke[2];
; #pragma unroll
;             for (int e = 0; e < 2; ++e) { const float bi = off + cs[i + e], kk = 1.0f - ex2(lf[i + e] * LOG2E_F); ke[e] = kk * ex2((blast - bi) * LOG2E_F);
;                 if (OUT) { QT[(16 * tq + i + e) * 136 + kx] = (bf16)f2bf(bf2f(qq[i + e]) * ex2(bi * LOG2E_F)); KI[(16 * tq + i + e) * 136 + kx] = (bf16)f2bf(kk * ex2(-bi * LOG2E_F)); } }
;             kew[i >> 1] = pk2(ke[0], ke[1]); vtw[i >> 1] = (unsigned)vv[i] | ((unsigned)vv[i + 1] << 16);
	v_lshl_or_b32 v34, v123, 16, v121
	global_load_ushort v121, v[38:39], off
	global_load_ushort v123, v[36:37], off
	s_waitcnt vmcnt(28)
	v_lshl_or_b32 v35, v127, 16, v125
	v_lshl_add_u64 v[36:37], s[66:67], 0, v[42:43]
	v_lshl_add_u64 v[38:39], s[66:67], 0, v[98:99]
	global_load_ushort v104, v[40:41], off
	global_load_ushort v105, v[38:39], off
	global_load_ushort v125, v[36:37], off
	v_lshl_add_u64 v[40:41], s[66:67], 0, v[106:107]
	v_lshl_add_u64 v[38:39], s[66:67], 0, v[44:45]
	global_load_ushort v106, v[40:41], off
	global_load_ushort v107, v[38:39], off
	v_lshl_add_u64 v[40:41], s[66:67], 0, v[100:101]
	v_lshl_add_u64 v[44:45], s[66:67], 0, v[114:115]
	v_lshl_add_u64 v[48:49], s[66:67], 0, v[110:111]
	v_lshl_add_u64 v[42:43], s[66:67], 0, v[112:113]
	global_load_ushort v112, v[44:45], off
	global_load_ushort v113, v[40:41], off
	v_lshl_add_u64 v[40:41], s[66:67], 0, v[116:117]
	v_lshl_add_u64 v[44:45], s[66:67], 0, v[102:103]
	global_load_ushort v110, v[48:49], off
	global_load_ushort v111, v[44:45], off
	global_load_ushort v114, v[40:41], off
	global_load_ushort v101, v[46:47], off
	v_add_f32_e32 v45, v120, v122
	v_add_f32_e32 v100, v45, v124
	v_add_f32_e32 v102, v100, v126
	s_waitcnt vmcnt(38)
	v_add_f32_e32 v103, v102, v128
	s_waitcnt vmcnt(36)
	v_add_f32_e32 v115, v103, v130
	s_waitcnt vmcnt(34)
	v_add_f32_e32 v116, v115, v132
	s_waitcnt vmcnt(32)
	v_add_f32_e32 v117, v116, v134
	v_lshl_or_b32 v36, v131, 16, v129
	s_waitcnt vmcnt(31)
	v_lshl_or_b32 v37, v135, 16, v133
	global_load_ushort v131, v[42:43], off
	v_mul_f32_e32 v44, 0x3fb8aa3b, v120
	v_exp_f32_e32 v98, v44
	s_waitcnt vmcnt(28)
	v_lshl_or_b32 v38, v139, 16, v137
	s_waitcnt vmcnt(25)
	v_lshl_or_b32 v39, v142, 16, v141
	s_waitcnt vmcnt(23)
	v_lshl_or_b32 v40, v118, 16, v143
	v_add_f32_e32 v118, v117, v136
	v_add_f32_e32 v127, v118, v138
	v_add_f32_e32 v129, v127, v140
	s_waitcnt vmcnt(22)
	v_add_f32_e32 v133, v129, v119
	s_waitcnt vmcnt(21)
	v_add_f32_e32 v135, v133, v144
	s_waitcnt vmcnt(20)
	v_add_f32_e32 v137, v135, v145
	s_waitcnt vmcnt(19)
	v_add_f32_e32 v139, v137, v146
	s_waitcnt vmcnt(18)
	v_add_f32_e32 v141, v139, v97
	ds_write_b32 v62, v141
	s_waitcnt lgkmcnt(0)
	s_barrier
	ds_read2st64_b32 v[42:43], v63 offset1:2
	ds_read2st64_b32 v[46:47], v63 offset0:4 offset1:6
	s_waitcnt vmcnt(16)
	v_lshl_or_b32 v41, v109, 16, v108
	s_waitcnt vmcnt(14)
	v_lshlrev_b32_e32 v99, 16, v148
	s_waitcnt lgkmcnt(1)
	v_add_f32_e32 v42, 0, v42
	v_cndmask_b32_e64 v44, v42, 0, s[8:9]
	v_add_f32_e32 v48, v43, v44
	v_cndmask_b32_e64 v44, v44, v48, s[10:11]
	v_add_f32_e32 v42, v42, v43
	s_waitcnt lgkmcnt(0)
	v_add_f32_e32 v43, v46, v44
	v_cndmask_b32_e64 v43, v44, v43, s[12:13]
	v_add_f32_e32 v44, v42, v46
	v_add_f32_e32 v42, v47, v43
	v_cndmask_b32_e64 v49, v43, v42, s[14:15]
	v_add_f32_e32 v43, v120, v49
	v_mov_b32_e32 v48, v47
	v_mul_f32_e32 v42, 0x3fb8aa3b, v43
	v_pk_add_f32 v[46:47], v[44:45], v[48:49]
	v_exp_f32_e32 v44, v42
	v_sub_f32_e32 v42, v46, v43
	v_mul_f32_e32 v43, 0xbfb8aa3b, v43
	v_exp_f32_e32 v48, v43
	v_mul_f32_e32 v43, 0x3fb8aa3b, v122
	v_mul_f32_e32 v44, v44, v99
	v_exp_f32_e32 v99, v43
	v_bfe_u32 v45, v44, 16, 1
	v_add3_u32 v44, v44, v45, s54
	ds_write_b16_d16_hi v72, v44
	v_pk_add_f32 v[44:45], v[98:99], 1.0 op_sel_hi:[1,0] neg_lo:[1,0] neg_hi:[1,0]
	v_sub_f32_e32 v43, v46, v47
	v_mul_f32_e32 v48, v44, v48
	v_mul_f32_e32 v42, 0x3fb8aa3b, v42
	v_mul_f32_e32 v43, 0x3fb8aa3b, v43
	v_bfe_u32 v98, v48, 16, 1
	v_exp_f32_e32 v42, v42
	v_exp_f32_e32 v43, v43
	v_add3_u32 v48, v48, v98, s54
	v_mul_f32_e32 v98, 0x3fb8aa3b, v47
	v_exp_f32_e32 v98, v98
	v_mul_f32_e32 v47, 0xbfb8aa3b, v47
	v_pk_mul_f32 v[42:43], v[44:45], v[42:43]
	v_lshlrev_b32_e32 v44, 16, v147
	v_exp_f32_e32 v47, v47
	v_mul_f32_e32 v44, v98, v44
	ds_write_b16_d16_hi v72, v48 offset:17408
	v_bfe_u32 v48, v44, 16, 1
	v_add3_u32 v44, v44, v48, s54
	v_cvt_pk_bf16_f32 v42, v42, v43
	v_add_f32_e32 v43, v100, v49
	ds_write_b16_d16_hi v73, v44 offset:272
	v_mul_f32_e32 v44, v45, v47
	v_mul_f32_e32 v47, 0x3fb8aa3b, v43
	v_bfe_u32 v45, v44, 16, 1
	v_exp_f32_e32 v47, v47
	v_add3_u32 v44, v44, v45, s54
	v_sub_f32_e32 v45, v46, v43
	v_mul_f32_e32 v45, 0x3fb8aa3b, v45
	v_exp_f32_e32 v98, v45
	s_waitcnt vmcnt(1)
	v_lshlrev_b32_e32 v45, 16, v101
	v_mul_f32_e32 v45, v47, v45
	v_bfe_u32 v47, v45, 16, 1
	v_add3_u32 v45, v45, v47, s54
	ds_write_b16_d16_hi v73, v44 offset:17680
	v_mul_f32_e32 v44, 0x3fb8aa3b, v124
	ds_write_b16_d16_hi v73, v45 offset:544
	v_mul_f32_e32 v45, 0x3fb8aa3b, v126
	v_exp_f32_e32 v44, v44
	v_mul_f32_e32 v43, 0xbfb8aa3b, v43
	v_exp_f32_e32 v45, v45
	v_exp_f32_e32 v43, v43
	v_add_f32_e32 v47, v102, v49
	v_sub_f32_e32 v48, v46, v47
	v_pk_add_f32 v[44:45], v[44:45], 1.0 op_sel_hi:[1,0] neg_lo:[1,0] neg_hi:[1,0]
	v_mul_f32_e32 v48, 0x3fb8aa3b, v48
	v_mul_f32_e32 v43, v44, v43
	v_exp_f32_e32 v99, v48
	v_bfe_u32 v48, v43, 16, 1
	v_add3_u32 v43, v43, v48, s54
	v_mul_f32_e32 v48, 0x3fb8aa3b, v47
	v_exp_f32_e32 v48, v48
	v_pk_mul_f32 v[98:99], v[44:45], v[98:99]
	v_mul_f32_e32 v44, 0xbfb8aa3b, v47
	ds_write_b16_d16_hi v73, v43 offset:17952
	v_lshlrev_b32_e32 v43, 16, v123
	v_exp_f32_e32 v44, v44
	v_mul_f32_e32 v43, v48, v43
	v_bfe_u32 v47, v43, 16, 1
	v_add3_u32 v43, v43, v47, s54
	ds_write_b16_d16_hi v73, v43 offset:816
	v_mul_f32_e32 v43, v45, v44
	v_add_f32_e32 v45, v103, v49
	v_mul_f32_e32 v48, 0x3fb8aa3b, v45
	v_exp_f32_e32 v48, v48
	v_bfe_u32 v44, v43, 16, 1
	v_sub_f32_e32 v47, v46, v45
	v_add3_u32 v43, v43, v44, s54
	v_mul_f32_e32 v47, 0x3fb8aa3b, v47
	ds_write_b16_d16_hi v73, v43 offset:18224
	v_cvt_pk_bf16_f32 v43, v98, v99
	v_exp_f32_e32 v98, v47
	v_lshlrev_b32_e32 v47, 16, v121
	v_mul_f32_e32 v47, v48, v47
; __device__ __forceinline__ unsigned f2bf(float f) { unsigned u = __builtin_bit_cast(unsigned, f); return (u + 0x7fffu + ((u >> 16) & 1u)) >> 16; }
; __device__ __forceinline__ unsigned pk2(float lo, float hi) { return pg8::cvt_pk_bf16(lo, hi); }
; __device__ __forceinline__ float ex2(float x) { return __builtin_amdgcn_exp2f(x); }
; template <bool OUT>
; __device__ __forceinline__ void hgrn_unit(int unit, LAS unsigned char* lds, const float* HLF, const bf16* HQ, const bf16* HV, const bf16* HG, bf16* MIX, float* UBUF, float* DTOT, const float* SST, gu32* rdy4 = nullptr) {
;     ...
;         for (int i = 0; i < 16; i += 2) {
;             float ke[2];
; #pragma unroll
;             for (int e = 0; e < 2; ++e) { const float bi = off + cs[i + e], kk = 1.0f - ex2(lf[i + e] * LOG2E_F); ke[e] = kk * ex2((blast - bi) * LOG2E_F);
;                 if (OUT) { QT[(16 * tq + i + e) * 136 + kx] = (bf16)f2bf(bf2f(qq[i + e]) * ex2(bi * LOG2E_F)); KI[(16 * tq + i + e) * 136 + kx] = (bf16)f2bf(kk * ex2(-bi * LOG2E_F)); } }
;             kew[i >> 1] = pk2(ke[0], ke[1]); vtw[i >> 1] = (unsigned)vv[i] | ((unsigned)vv[i + 1] << 16);
	v_bfe_u32 v48, v47, 16, 1
	v_add3_u32 v47, v47, v48, s54
	v_mul_f32_e32 v45, 0xbfb8aa3b, v45
	v_mul_f32_e32 v44, 0x3fb8aa3b, v128
	ds_write_b16_d16_hi v73, v47 offset:1088
	v_exp_f32_e32 v47, v45
	v_mul_f32_e32 v45, 0x3fb8aa3b, v130
	v_exp_f32_e32 v44, v44
	v_exp_f32_e32 v45, v45
	v_add_f32_e32 v48, v115, v49
	v_sub_f32_e32 v99, v46, v48
	v_mul_f32_e32 v99, 0x3fb8aa3b, v99
	v_pk_add_f32 v[44:45], v[44:45], 1.0 op_sel_hi:[1,0] neg_lo:[1,0] neg_hi:[1,0]
	v_exp_f32_e32 v99, v99
	v_mul_f32_e32 v47, v44, v47
	v_bfe_u32 v100, v47, 16, 1
	v_add3_u32 v47, v47, v100, s54
	v_mul_f32_e32 v100, 0x3fb8aa3b, v48
	v_exp_f32_e32 v100, v100
	ds_write_b16_d16_hi v73, v47 offset:18496
	v_mul_f32_e32 v47, 0xbfb8aa3b, v48
	v_pk_mul_f32 v[98:99], v[44:45], v[98:99]
	v_lshlrev_b32_e32 v44, 16, v125
	v_exp_f32_e32 v47, v47
	v_mul_f32_e32 v44, v100, v44
	v_bfe_u32 v48, v44, 16, 1
	v_add3_u32 v44, v44, v48, s54
	ds_write_b16_d16_hi v73, v44 offset:1360
	v_mul_f32_e32 v44, v45, v47
	v_bfe_u32 v45, v44, 16, 1
	v_add3_u32 v44, v44, v45, s54
	v_add_f32_e32 v45, v116, v49
	v_mul_f32_e32 v48, 0x3fb8aa3b, v45
	v_mul_f32_e32 v47, 0x3fb8aa3b, v132
	v_exp_f32_e32 v48, v48
	ds_write_b16_d16_hi v73, v44 offset:18768
	v_cvt_pk_bf16_f32 v44, v98, v99
	v_exp_f32_e32 v98, v47
	v_sub_f32_e32 v47, v46, v45
	v_mul_f32_e32 v47, 0x3fb8aa3b, v47
	v_exp_f32_e32 v100, v47
	v_lshlrev_b32_e32 v47, 16, v105
	v_mul_f32_e32 v47, v48, v47
	v_bfe_u32 v48, v47, 16, 1
	v_add3_u32 v47, v47, v48, s54
	v_mul_f32_e32 v48, 0x3fb8aa3b, v134
	v_mul_f32_e32 v45, 0xbfb8aa3b, v45
	v_exp_f32_e32 v99, v48
	v_exp_f32_e32 v45, v45
	ds_write_b16_d16_hi v73, v47 offset:1632
	v_add_f32_e32 v47, v117, v49
	v_sub_f32_e32 v48, v46, v47
	v_pk_add_f32 v[98:99], v[98:99], 1.0 op_sel_hi:[1,0] neg_lo:[1,0] neg_hi:[1,0]
	v_mul_f32_e32 v48, 0x3fb8aa3b, v48
	v_mul_f32_e32 v45, v98, v45
	v_exp_f32_e32 v101, v48
	v_bfe_u32 v48, v45, 16, 1
	v_add3_u32 v45, v45, v48, s54
	v_mul_f32_e32 v48, 0x3fb8aa3b, v47
	v_exp_f32_e32 v48, v48
	v_mul_f32_e32 v47, 0xbfb8aa3b, v47
	ds_write_b16_d16_hi v73, v45 offset:19040
	v_lshlrev_b32_e32 v45, 16, v104
	v_exp_f32_e32 v47, v47
	v_mul_f32_e32 v45, v48, v45
	v_bfe_u32 v48, v45, 16, 1
	v_add3_u32 v45, v45, v48, s54
	ds_write_b16_d16_hi v73, v45 offset:1904
	v_mul_f32_e32 v45, v99, v47
	v_bfe_u32 v47, v45, 16, 1
	v_add3_u32 v45, v45, v47, s54
	v_add_f32_e32 v47, v118, v49
	v_pk_mul_f32 v[100:101], v[98:99], v[100:101]
	v_mul_f32_e32 v99, 0x3fb8aa3b, v47
	v_mul_f32_e32 v48, 0x3fb8aa3b, v136
	v_exp_f32_e32 v99, v99
	v_exp_f32_e32 v98, v48
	v_sub_f32_e32 v48, v46, v47
	v_mul_f32_e32 v48, 0x3fb8aa3b, v48
	ds_write_b16_d16_hi v73, v45 offset:19312
	v_cvt_pk_bf16_f32 v45, v100, v101
	v_exp_f32_e32 v100, v48
	v_lshlrev_b32_e32 v48, 16, v107
	v_mul_f32_e32 v48, v99, v48
	v_bfe_u32 v99, v48, 16, 1
	v_add3_u32 v48, v48, v99, s54
	v_mul_f32_e32 v99, 0x3fb8aa3b, v138
	v_mul_f32_e32 v47, 0xbfb8aa3b, v47
	v_exp_f32_e32 v99, v99
	v_exp_f32_e32 v47, v47
	ds_write_b16_d16_hi v73, v48 offset:2176
	v_add_f32_e32 v48, v127, v49
	v_pk_add_f32 v[98:99], v[98:99], 1.0 op_sel_hi:[1,0] neg_lo:[1,0] neg_hi:[1,0]
	v_sub_f32_e32 v101, v46, v48
	v_mul_f32_e32 v47, v98, v47
	v_bfe_u32 v102, v47, 16, 1
	v_add3_u32 v47, v47, v102, s54
	v_mul_f32_e32 v102, 0x3fb8aa3b, v48
	v_mul_f32_e32 v101, 0x3fb8aa3b, v101
	v_exp_f32_e32 v102, v102
	v_exp_f32_e32 v101, v101
	v_mul_f32_e32 v48, 0xbfb8aa3b, v48
	ds_write_b16_d16_hi v73, v47 offset:19584
	v_lshlrev_b32_e32 v47, 16, v106
	v_exp_f32_e32 v48, v48
	v_mul_f32_e32 v47, v102, v47
	v_pk_mul_f32 v[100:101], v[98:99], v[100:101]
	v_bfe_u32 v98, v47, 16, 1
	v_add3_u32 v47, v47, v98, s54
	ds_write_b16_d16_hi v73, v47 offset:2448
	v_mul_f32_e32 v47, v99, v48
	v_bfe_u32 v48, v47, 16, 1
	v_add3_u32 v47, v47, v48, s54
	ds_write_b16_d16_hi v73, v47 offset:19856
	v_add_f32_e32 v47, v129, v49
	v_mul_f32_e32 v99, 0x3fb8aa3b, v47
	v_mul_f32_e32 v48, 0x3fb8aa3b, v140
	v_exp_f32_e32 v99, v99
	v_cvt_pk_bf16_f32 v98, v100, v101
	v_exp_f32_e32 v100, v48
	v_sub_f32_e32 v48, v46, v47
	v_mul_f32_e32 v48, 0x3fb8aa3b, v48
	v_exp_f32_e32 v102, v48
	s_waitcnt vmcnt(0)
; #define LAS __attribute__((address_space(3)))
; __device__ __forceinline__ unsigned f2bf(float f) { unsigned u = __builtin_bit_cast(unsigned, f); return (u + 0x7fffu + ((u >> 16) & 1u)) >> 16; }
; __device__ __forceinline__ unsigned pk2(float lo, float hi) { return pg8::cvt_pk_bf16(lo, hi); }
; __device__ __forceinline__ float ex2(float x) { return __builtin_amdgcn_exp2f(x); }
; template <bool OUT>
; __device__ __forceinline__ void hgrn_unit(int unit, LAS unsigned char* lds, const float* HLF, const bf16* HQ, const bf16* HV, const bf16* HG, bf16* MIX, float* UBUF, float* DTOT, const float* SST, gu32* rdy4 = nullptr) {
;     ...
;         for (int i = 0; i < 16; i += 2) {
;             float ke[2];
; #pragma unroll
;             for (int e = 0; e < 2; ++e) { const float bi = off + cs[i + e], kk = 1.0f - ex2(lf[i + e] * LOG2E_F); ke[e] = kk * ex2((blast - bi) * LOG2E_F);
;                 if (OUT) { QT[(16 * tq + i + e) * 136 + kx] = (bf16)f2bf(bf2f(qq[i + e]) * ex2(bi * LOG2E_F)); KI[(16 * tq + i + e) * 136 + kx] = (bf16)f2bf(kk * ex2(-bi * LOG2E_F)); } }
;             kew[i >> 1] = pk2(ke[0], ke[1]); vtw[i >> 1] = (unsigned)vv[i] | ((unsigned)vv[i + 1] << 16);
;         }
;         *(LAS v4u*)(KET + kx * 72 + 16 * tq) = (v4u){kew[0], kew[1], kew[2], kew[3]}; *(LAS v4u*)(KET + kx * 72 + 16 * tq + 8) = (v4u){kew[4], kew[5], kew[6], kew[7]};
;         *(LAS v4u*)(VT + kx * 72 + 16 * tq) = (v4u){vtw[0], vtw[1], vtw[2], vtw[3]}; *(LAS v4u*)(VT + kx * 72 + 16 * tq + 8) = (v4u){vtw[4], vtw[5], vtw[6], vtw[7]};
;         if (tq == 0) { DEC[kx] = ex2(blast * LOG2E_F); dacc += blast; }
;     ...
;             const v4u g0 = *(const v4u*)(HG + (size_t)row * 512 + col0 + 16 * seg), g1 = *(const v4u*)(HG + (size_t)row * 512 + col0 + 16 * seg + 8);
	v_add_u32_e32 v208, s58, v81
	v_ashrrev_i32_e32 v209, 31, v208
	v_lshlrev_b64 v[208:209], 10, v[208:209]
	v_lshl_add_u64 v[208:209], v[60:61], 0, v[208:209]
	global_load_dwordx4 v[200:203], v[208:209], off
	global_load_dwordx4 v[204:207], v[208:209], off offset:16
	v_mbcnt_lo_u32_b32 v210, -1, 0
	v_mbcnt_hi_u32_b32 v210, -1, v210
	v_lshrrev_b32_e32 v211, 1, v210
	v_and_b32_e32 v212, 15, v210
	v_cmp_gt_u32_e32 vcc, 32, v210
	v_and_b32_e32 v222, 1, v210
	v_lshlrev_b32_e32 v222, 7, v222
	v_cndmask_b32_e32 v211, v212, v211, vcc
	v_add3_u32 v211, v211, v82, s58
	v_add_u32_e32 v211, 64, v211
	v_and_b32_e32 v212, 0xffffffc0, v58
	v_lshl_or_b32 v212, v211, 9, v212
	v_mov_b32_e32 v213, 0
	v_mov_b32_e32 v223, 0
	v_lshl_add_u64 v[214:215], v[212:213], 2, s[64:65]
	v_lshl_add_u64 v[216:217], v[212:213], 1, s[68:69]
	v_lshl_add_u64 v[218:219], v[212:213], 1, s[66:67]
	v_lshl_add_u64 v[214:215], v[214:215], 0, v[222:223]
	v_cmp_gt_u32_e32 vcc, 48, v210
	s_nop 1
	v_cndmask_b32_e32 v216, v218, v216, vcc
	v_cndmask_b32_e32 v217, v219, v217, vcc
	v_cmp_gt_u32_e32 vcc, 32, v210
	s_nop 1
	v_cndmask_b32_e32 v216, v216, v214, vcc
	v_cndmask_b32_e32 v217, v217, v215, vcc
	global_load_dword v224, v[216:217], off
	v_lshlrev_b32_e32 v48, 16, v131
	v_mul_f32_e32 v48, v99, v48
	v_bfe_u32 v99, v48, 16, 1
	v_add3_u32 v48, v48, v99, s54
	v_mul_f32_e32 v99, 0x3fb8aa3b, v119
	v_mul_f32_e32 v47, 0xbfb8aa3b, v47
	v_exp_f32_e32 v101, v99
	v_exp_f32_e32 v47, v47
	ds_write_b16_d16_hi v73, v48 offset:2720
	v_add_f32_e32 v48, v133, v49
	v_sub_f32_e32 v99, v46, v48
	v_pk_add_f32 v[100:101], v[100:101], 1.0 op_sel_hi:[1,0] neg_lo:[1,0] neg_hi:[1,0]
	v_mul_f32_e32 v99, 0x3fb8aa3b, v99
	v_mul_f32_e32 v47, v100, v47
	v_exp_f32_e32 v103, v99
	v_bfe_u32 v99, v47, 16, 1
	v_add3_u32 v47, v47, v99, s54
	v_mul_f32_e32 v99, 0x3fb8aa3b, v48
	v_exp_f32_e32 v99, v99
	v_mul_f32_e32 v48, 0xbfb8aa3b, v48
	ds_write_b16_d16_hi v73, v47 offset:20128
	v_lshlrev_b32_e32 v47, 16, v113
	v_exp_f32_e32 v48, v48
	v_mul_f32_e32 v47, v99, v47
	v_bfe_u32 v99, v47, 16, 1
	v_add3_u32 v47, v47, v99, s54
	ds_write_b16_d16_hi v73, v47 offset:2992
	v_mul_f32_e32 v47, v101, v48
	v_bfe_u32 v48, v47, 16, 1
	v_add3_u32 v47, v47, v48, s54
	ds_write_b16_d16_hi v73, v47 offset:20400
	v_add_f32_e32 v47, v135, v49
	v_pk_mul_f32 v[102:103], v[100:101], v[102:103]
	v_mul_f32_e32 v101, 0x3fb8aa3b, v47
	v_mul_f32_e32 v48, 0x3fb8aa3b, v144
	v_exp_f32_e32 v101, v101
	v_exp_f32_e32 v100, v48
	v_sub_f32_e32 v48, v46, v47
	v_mul_f32_e32 v48, 0x3fb8aa3b, v48
	v_cvt_pk_bf16_f32 v99, v102, v103
	v_exp_f32_e32 v102, v48
	v_lshlrev_b32_e32 v48, 16, v112
	v_mul_f32_e32 v48, v101, v48
	v_bfe_u32 v101, v48, 16, 1
	v_add3_u32 v48, v48, v101, s54
	v_mul_f32_e32 v101, 0x3fb8aa3b, v145
	v_mul_f32_e32 v47, 0xbfb8aa3b, v47
	v_exp_f32_e32 v101, v101
	v_exp_f32_e32 v47, v47
	ds_write_b16_d16_hi v73, v48 offset:3264
	v_add_f32_e32 v48, v137, v49
	v_pk_add_f32 v[100:101], v[100:101], 1.0 op_sel_hi:[1,0] neg_lo:[1,0] neg_hi:[1,0]
	v_sub_f32_e32 v103, v46, v48
	v_mul_f32_e32 v47, v100, v47
	v_bfe_u32 v104, v47, 16, 1
	v_add3_u32 v47, v47, v104, s54
	v_mul_f32_e32 v104, 0x3fb8aa3b, v48
	v_mul_f32_e32 v103, 0x3fb8aa3b, v103
	v_exp_f32_e32 v104, v104
	v_exp_f32_e32 v103, v103
	v_mul_f32_e32 v48, 0xbfb8aa3b, v48
	ds_write_b16_d16_hi v73, v47 offset:20672
	v_lshlrev_b32_e32 v47, 16, v114
	v_exp_f32_e32 v48, v48
	v_mul_f32_e32 v47, v104, v47
	v_pk_mul_f32 v[102:103], v[100:101], v[102:103]
	v_bfe_u32 v100, v47, 16, 1
	v_add3_u32 v47, v47, v100, s54
	ds_write_b16_d16_hi v73, v47 offset:3536
	v_mul_f32_e32 v47, v101, v48
	v_bfe_u32 v48, v47, 16, 1
	v_add3_u32 v47, v47, v48, s54
	ds_write_b16_d16_hi v73, v47 offset:20944
	v_add_f32_e32 v47, v139, v49
	v_cvt_pk_bf16_f32 v100, v102, v103
	v_mul_f32_e32 v102, 0x3fb8aa3b, v47
	v_exp_f32_e32 v103, v102
	v_sub_f32_e32 v101, v46, v47
	v_mul_f32_e32 v101, 0x3fb8aa3b, v101
	v_exp_f32_e32 v102, v101
	v_lshlrev_b32_e32 v101, 16, v111
	v_mul_f32_e32 v101, v103, v101
	v_bfe_u32 v103, v101, 16, 1
	v_add3_u32 v101, v101, v103, s54
	v_mul_f32_e32 v48, 0x3fb8aa3b, v146
	ds_write_b16_d16_hi v73, v101 offset:3808
	v_add_f32_e32 v101, v141, v49
	v_mul_f32_e32 v49, 0x3fb8aa3b, v97
	v_exp_f32_e32 v48, v48
	v_mul_f32_e32 v47, 0xbfb8aa3b, v47
	v_exp_f32_e32 v49, v49
	v_exp_f32_e32 v47, v47
	v_sub_f32_e32 v97, v46, v101
	v_mul_f32_e32 v97, 0x3fb8aa3b, v97
	v_pk_add_f32 v[48:49], v[48:49], 1.0 op_sel_hi:[1,0] neg_lo:[1,0] neg_hi:[1,0]
	v_exp_f32_e32 v103, v97
	v_mul_f32_e32 v47, v48, v47
	v_bfe_u32 v97, v47, 16, 1
	v_add3_u32 v47, v47, v97, s54
	v_mul_f32_e32 v97, 0x3fb8aa3b, v101
	v_exp_f32_e32 v97, v97
	v_pk_mul_f32 v[102:103], v[48:49], v[102:103]
	v_mul_f32_e32 v48, 0xbfb8aa3b, v101
	ds_write_b16_d16_hi v73, v47 offset:21216
	v_lshlrev_b32_e32 v47, 16, v110
	v_exp_f32_e32 v48, v48
	v_mul_f32_e32 v47, v97, v47
	v_bfe_u32 v97, v47, 16, 1
	v_add3_u32 v47, v47, v97, s54
	ds_write_b16_d16_hi v74, v47
	v_mul_f32_e32 v47, v49, v48
	v_bfe_u32 v48, v47, 16, 1
	v_add3_u32 v47, v47, v48, s54
	ds_write_b16_d16_hi v74, v47 offset:17408
	v_cvt_pk_bf16_f32 v101, v102, v103
	ds_write_b128 v64, v[42:45] offset:34816
	ds_write_b128 v64, v[98:101] offset:34832
	ds_write_b128 v64, v[34:37] offset:53248
	ds_write_b128 v64, v[38:41] offset:53264
	s_and_saveexec_b64 s[82:83], s[8:9]
	s_cbranch_execz .LBB0_588
	v_mul_f32_e32 v34, 0x3fb8aa3b, v46
	v_exp_f32_e32 v34, v34
	ds_write_b32 v65, v34
